# k42 + SwiGLU column-scale loads hoisted to unit head (epilogue vmcnt(0) dropped) + attention bias LDS reads hoisted into the QK MFMA gaps
# speedup vs baseline: 1.0037x; 1.0014x over previous
.LBB0_444:
	s_lshl_b32 s100, s24, 3
	s_or_b32 s100, s100, s70
	s_ashr_i32 s101, s100, 31
	s_lshl_b64 s[100:101], s[100:101], 2
	s_add_u32 s100, s26, s100
	s_addc_u32 s101, s69, s101
	global_load_dword v232, v1, s[100:101] sc1
	global_load_dword v233, v1, s[100:101] offset:16 sc1
	s_add_u32 s48, s46, 0x20080
	s_addc_u32 s49, s47, 0
	s_add_u32 s25, s50, 0x100
	s_addc_u32 s64, s51, 0
	s_mov_b32 s65, -2
	s_add_u32 s46, s48, 0xfffe0080
	s_addc_u32 s47, s49, -1
	s_add_i32 s84, 0, 0x10000
	s_cmp_eq_u32 s65, 4
	s_cselect_b32 s47, s15, s47
	s_cselect_b32 s46, s14, s46
	v_add_u32_e32 v0, s84, v147
	s_cselect_b32 s51, s17, s64
	s_cselect_b32 s50, s16, s25
	s_add_i32 s86, 0, 0x14000
	ds_read_b128 v[150:153], v0
	ds_read_b128 v[154:157], v0 offset:1024
	ds_read_b128 v[158:161], v0 offset:2048
	ds_read_b128 v[162:165], v0 offset:3072
	ds_read_b128 v[166:169], v0 offset:16384
	ds_read_b128 v[170:173], v0 offset:17408
	ds_read_b128 v[174:177], v0 offset:18432
	ds_read_b128 v[178:181], v0 offset:19456
	ds_read_b128 v[182:185], v148
	ds_read_b128 v[186:189], v148 offset:1024
	ds_read_b128 v[190:193], v148 offset:2048
	ds_read_b128 v[194:197], v148 offset:3072
	ds_read_b128 v[198:201], v148 offset:4096
	ds_read_b128 v[202:205], v148 offset:5120
	ds_read_b128 v[206:209], v148 offset:6144
	ds_read_b128 v[210:213], v148 offset:7168
	s_add_i32 m0, s59, 0xc000
	s_nop 0
	global_load_lds_dwordx4 v132, s[48:49]
	s_add_i32 m0, s59, 0xe000
	s_nop 0
	global_load_lds_dwordx4 v133, s[48:49]
	s_waitcnt vmcnt(8)
	s_waitcnt lgkmcnt(0)
	s_setprio 1
	s_barrier
	v_mfma_i32_16x16x64_i8 v[126:129], v[150:153], v[182:185], 0
	v_mfma_i32_16x16x64_i8 v[122:125], v[158:161], v[182:185], 0
	v_mfma_i32_16x16x64_i8 v[110:113], v[150:153], v[190:193], 0
	v_mfma_i32_16x16x64_i8 v[106:109], v[158:161], v[190:193], 0
	v_mfma_i32_16x16x64_i8 v[94:97], v[150:153], v[198:201], 0
	v_mfma_i32_16x16x64_i8 v[90:93], v[158:161], v[198:201], 0
	v_mfma_i32_16x16x64_i8 v[78:81], v[150:153], v[206:209], 0
	v_mfma_i32_16x16x64_i8 v[74:77], v[158:161], v[206:209], 0
	v_mfma_i32_16x16x64_i8 v[126:129], v[154:157], v[186:189], v[126:129]
	v_mfma_i32_16x16x64_i8 v[122:125], v[162:165], v[186:189], v[122:125]
	v_mfma_i32_16x16x64_i8 v[110:113], v[154:157], v[194:197], v[110:113]
	v_mfma_i32_16x16x64_i8 v[106:109], v[162:165], v[194:197], v[106:109]
	v_mfma_i32_16x16x64_i8 v[94:97], v[154:157], v[202:205], v[94:97]
	v_mfma_i32_16x16x64_i8 v[90:93], v[162:165], v[202:205], v[90:93]
	v_mfma_i32_16x16x64_i8 v[78:81], v[154:157], v[210:213], v[78:81]
	v_mfma_i32_16x16x64_i8 v[74:77], v[162:165], v[210:213], v[74:77]
	s_setprio 0
	s_setprio 1
	v_mfma_i32_16x16x64_i8 v[118:121], v[166:169], v[182:185], 0
	v_mfma_i32_16x16x64_i8 v[114:117], v[174:177], v[182:185], 0
	v_mfma_i32_16x16x64_i8 v[102:105], v[166:169], v[190:193], 0
	v_mfma_i32_16x16x64_i8 v[98:101], v[174:177], v[190:193], 0
	v_mfma_i32_16x16x64_i8 v[86:89], v[166:169], v[198:201], 0
	v_mfma_i32_16x16x64_i8 v[82:85], v[174:177], v[198:201], 0
	v_mfma_i32_16x16x64_i8 v[70:73], v[166:169], v[206:209], 0
	v_mfma_i32_16x16x64_i8 v[66:69], v[174:177], v[206:209], 0
	v_mfma_i32_16x16x64_i8 v[118:121], v[170:173], v[186:189], v[118:121]
	v_mfma_i32_16x16x64_i8 v[114:117], v[178:181], v[186:189], v[114:117]
	v_mfma_i32_16x16x64_i8 v[102:105], v[170:173], v[194:197], v[102:105]
	v_mfma_i32_16x16x64_i8 v[98:101], v[178:181], v[194:197], v[98:101]
	v_mfma_i32_16x16x64_i8 v[86:89], v[170:173], v[202:205], v[86:89]
	v_mfma_i32_16x16x64_i8 v[82:85], v[178:181], v[202:205], v[82:85]
	v_mfma_i32_16x16x64_i8 v[70:73], v[170:173], v[210:213], v[70:73]
	v_mfma_i32_16x16x64_i8 v[66:69], v[178:181], v[210:213], v[66:69]
	s_setprio 0
	s_barrier
	s_add_i32 s84, s84, s40
	ds_read_b128 v[182:185], v148 offset:16384
	ds_read_b128 v[186:189], v148 offset:17408
	ds_read_b128 v[190:193], v148 offset:18432
	ds_read_b128 v[194:197], v148 offset:19456
	ds_read_b128 v[198:201], v148 offset:20480
	ds_read_b128 v[202:205], v148 offset:21504
	ds_read_b128 v[206:209], v148 offset:22528
	ds_read_b128 v[210:213], v148 offset:23552
	s_mov_b32 m0, s84
	s_nop 0
	global_load_lds_dwordx4 v143, s[50:51]
	s_add_i32 m0, s84, 0x2000
	s_add_u32 s84, s50, 0x20000
	global_load_lds_dwordx4 v144, s[50:51]
	s_addc_u32 s85, s51, 0
	s_add_i32 s86, s86, s40
	s_mov_b32 m0, s86
	s_nop 0
	global_load_lds_dwordx4 v143, s[84:85]
	s_add_i32 m0, s86, 0x2000
	s_nop 0
	global_load_lds_dwordx4 v144, s[84:85]
	s_mov_b32 m0, s59
	s_nop 0
	global_load_lds_dwordx4 v132, s[46:47]
	s_mov_b32 m0, s60
	s_nop 0
	global_load_lds_dwordx4 v133, s[46:47]
	s_waitcnt vmcnt(8)
	s_waitcnt lgkmcnt(0)
	s_setprio 1
	s_barrier
	v_mfma_i32_16x16x64_i8 v[62:65], v[150:153], v[182:185], 0
	v_mfma_i32_16x16x64_i8 v[58:61], v[158:161], v[182:185], 0
	v_mfma_i32_16x16x64_i8 v[46:49], v[150:153], v[190:193], 0
	v_mfma_i32_16x16x64_i8 v[42:45], v[158:161], v[190:193], 0
	v_mfma_i32_16x16x64_i8 v[30:33], v[150:153], v[198:201], 0
	v_mfma_i32_16x16x64_i8 v[26:29], v[158:161], v[198:201], 0
	v_mfma_i32_16x16x64_i8 v[14:17], v[150:153], v[206:209], 0
	v_mfma_i32_16x16x64_i8 v[10:13], v[158:161], v[206:209], 0
	v_mfma_i32_16x16x64_i8 v[62:65], v[154:157], v[186:189], v[62:65]
	v_mfma_i32_16x16x64_i8 v[58:61], v[162:165], v[186:189], v[58:61]
	v_mfma_i32_16x16x64_i8 v[46:49], v[154:157], v[194:197], v[46:49]
	v_mfma_i32_16x16x64_i8 v[42:45], v[162:165], v[194:197], v[42:45]
	v_mfma_i32_16x16x64_i8 v[30:33], v[154:157], v[202:205], v[30:33]
	v_mfma_i32_16x16x64_i8 v[26:29], v[162:165], v[202:205], v[26:29]
	v_mfma_i32_16x16x64_i8 v[14:17], v[154:157], v[210:213], v[14:17]
	v_mfma_i32_16x16x64_i8 v[10:13], v[162:165], v[210:213], v[10:13]
	s_setprio 0
	s_setprio 1
	v_mfma_i32_16x16x64_i8 v[54:57], v[166:169], v[182:185], 0
	v_mfma_i32_16x16x64_i8 v[50:53], v[174:177], v[182:185], 0
	v_mfma_i32_16x16x64_i8 v[38:41], v[166:169], v[190:193], 0
	v_mfma_i32_16x16x64_i8 v[34:37], v[174:177], v[190:193], 0
	v_mfma_i32_16x16x64_i8 v[22:25], v[166:169], v[198:201], 0
	v_mfma_i32_16x16x64_i8 v[18:21], v[174:177], v[198:201], 0
	v_mfma_i32_16x16x64_i8 v[6:9], v[166:169], v[206:209], 0
	v_mfma_i32_16x16x64_i8 v[2:5], v[174:177], v[206:209], 0
	v_mfma_i32_16x16x64_i8 v[54:57], v[170:173], v[186:189], v[54:57]
	v_mfma_i32_16x16x64_i8 v[50:53], v[178:181], v[186:189], v[50:53]
	v_mfma_i32_16x16x64_i8 v[38:41], v[170:173], v[194:197], v[38:41]
	v_mfma_i32_16x16x64_i8 v[34:37], v[178:181], v[194:197], v[34:37]
	v_mfma_i32_16x16x64_i8 v[22:25], v[170:173], v[202:205], v[22:25]
	v_mfma_i32_16x16x64_i8 v[18:21], v[178:181], v[202:205], v[18:21]
	v_mfma_i32_16x16x64_i8 v[6:9], v[170:173], v[210:213], v[6:9]
	v_mfma_i32_16x16x64_i8 v[2:5], v[178:181], v[210:213], v[2:5]
	s_setprio 0
	s_barrier
	s_add_i32 s86, 0, 0x18000
	s_add_i32 s87, 0, 0x1c000
	ds_read_b128 v[150:153], v0 offset:32768
	ds_read_b128 v[154:157], v0 offset:33792
	ds_read_b128 v[158:161], v0 offset:34816
	ds_read_b128 v[162:165], v0 offset:35840
	ds_read_b128 v[166:169], v0 offset:49152
	ds_read_b128 v[170:173], v0 offset:50176
	ds_read_b128 v[174:177], v0 offset:51200
	ds_read_b128 v[178:181], v0 offset:52224
	s_add_u32 s84, s46, 0x20000
	s_mov_b32 m0, s61
	ds_read_b128 v[182:185], v148 offset:32768
	ds_read_b128 v[186:189], v148 offset:33792
	ds_read_b128 v[190:193], v148 offset:34816
	ds_read_b128 v[194:197], v148 offset:35840
	ds_read_b128 v[198:201], v148 offset:36864
	ds_read_b128 v[202:205], v148 offset:37888
	ds_read_b128 v[206:209], v148 offset:38912
	ds_read_b128 v[210:213], v148 offset:39936
	s_addc_u32 s85, s47, 0
	s_nop 0
	global_load_lds_dwordx4 v132, s[84:85]
	s_mov_b32 m0, s66
	s_nop 0
	global_load_lds_dwordx4 v133, s[84:85]
	s_waitcnt vmcnt(8)
	s_waitcnt lgkmcnt(0)
	s_setprio 1
	s_barrier
	v_mfma_i32_16x16x64_i8 v[126:129], v[150:153], v[182:185], v[126:129]
	v_mfma_i32_16x16x64_i8 v[122:125], v[158:161], v[182:185], v[122:125]
	v_mfma_i32_16x16x64_i8 v[110:113], v[150:153], v[190:193], v[110:113]
	v_mfma_i32_16x16x64_i8 v[106:109], v[158:161], v[190:193], v[106:109]
	v_mfma_i32_16x16x64_i8 v[94:97], v[150:153], v[198:201], v[94:97]
	v_mfma_i32_16x16x64_i8 v[90:93], v[158:161], v[198:201], v[90:93]
	v_mfma_i32_16x16x64_i8 v[78:81], v[150:153], v[206:209], v[78:81]
	v_mfma_i32_16x16x64_i8 v[74:77], v[158:161], v[206:209], v[74:77]
	v_mfma_i32_16x16x64_i8 v[126:129], v[154:157], v[186:189], v[126:129]
	v_mfma_i32_16x16x64_i8 v[122:125], v[162:165], v[186:189], v[122:125]
	v_mfma_i32_16x16x64_i8 v[110:113], v[154:157], v[194:197], v[110:113]
	v_mfma_i32_16x16x64_i8 v[106:109], v[162:165], v[194:197], v[106:109]
	v_mfma_i32_16x16x64_i8 v[94:97], v[154:157], v[202:205], v[94:97]
	v_mfma_i32_16x16x64_i8 v[90:93], v[162:165], v[202:205], v[90:93]
	v_mfma_i32_16x16x64_i8 v[78:81], v[154:157], v[210:213], v[78:81]
	v_mfma_i32_16x16x64_i8 v[74:77], v[162:165], v[210:213], v[74:77]
	s_setprio 0
	s_setprio 1
	v_mfma_i32_16x16x64_i8 v[118:121], v[166:169], v[182:185], v[118:121]
	v_mfma_i32_16x16x64_i8 v[114:117], v[174:177], v[182:185], v[114:117]
	v_mfma_i32_16x16x64_i8 v[102:105], v[166:169], v[190:193], v[102:105]
	v_mfma_i32_16x16x64_i8 v[98:101], v[174:177], v[190:193], v[98:101]
	v_mfma_i32_16x16x64_i8 v[86:89], v[166:169], v[198:201], v[86:89]
	v_mfma_i32_16x16x64_i8 v[82:85], v[174:177], v[198:201], v[82:85]
	v_mfma_i32_16x16x64_i8 v[70:73], v[166:169], v[206:209], v[70:73]
	v_mfma_i32_16x16x64_i8 v[66:69], v[174:177], v[206:209], v[66:69]
	v_mfma_i32_16x16x64_i8 v[118:121], v[170:173], v[186:189], v[118:121]
	v_mfma_i32_16x16x64_i8 v[114:117], v[178:181], v[186:189], v[114:117]
	v_mfma_i32_16x16x64_i8 v[102:105], v[170:173], v[194:197], v[102:105]
	v_mfma_i32_16x16x64_i8 v[98:101], v[178:181], v[194:197], v[98:101]
	v_mfma_i32_16x16x64_i8 v[86:89], v[170:173], v[202:205], v[86:89]
	v_mfma_i32_16x16x64_i8 v[82:85], v[178:181], v[202:205], v[82:85]
	v_mfma_i32_16x16x64_i8 v[70:73], v[170:173], v[210:213], v[70:73]
	v_mfma_i32_16x16x64_i8 v[66:69], v[178:181], v[210:213], v[66:69]
	s_setprio 0
	s_barrier
	ds_read_b128 v[182:185], v148 offset:49152
	ds_read_b128 v[186:189], v148 offset:50176
	ds_read_b128 v[190:193], v148 offset:51200
	ds_read_b128 v[194:197], v148 offset:52224
	ds_read_b128 v[198:201], v148 offset:53248
	ds_read_b128 v[202:205], v148 offset:54272
	ds_read_b128 v[206:209], v148 offset:55296
	ds_read_b128 v[210:213], v148 offset:56320
	s_add_i32 s84, s86, s40
	s_add_u32 s100, s50, s38
	s_addc_u32 s101, s51, s39
	s_mov_b32 m0, s84
	s_nop 0
	global_load_lds_dwordx4 v143, s[100:101]
	s_add_i32 m0, s84, 0x2000
	s_nop 0
	s_add_u32 s50, s50, 0x20080
	s_addc_u32 s51, s51, 0
	s_add_i32 s84, s87, s40
	global_load_lds_dwordx4 v144, s[100:101]
	s_mov_b32 m0, s84
	s_nop 0
	global_load_lds_dwordx4 v143, s[50:51]
	s_add_i32 m0, s84, 0x2000
	s_nop 0
	global_load_lds_dwordx4 v144, s[50:51]
	s_mov_b32 m0, s75
	s_add_u32 s100, s46, s38
	s_addc_u32 s101, s47, s39
	v_mov_b32_e32 v0, v133
	global_load_lds_dwordx4 v132, s[100:101]
	s_mov_b32 m0, s78
	s_nop 0
	global_load_lds_dwordx4 v133, s[100:101]
	s_waitcnt vmcnt(8)
	s_waitcnt lgkmcnt(0)
	s_setprio 1
	s_barrier
	v_mfma_i32_16x16x64_i8 v[62:65], v[150:153], v[182:185], v[62:65]
	v_mfma_i32_16x16x64_i8 v[58:61], v[158:161], v[182:185], v[58:61]
	v_mfma_i32_16x16x64_i8 v[46:49], v[150:153], v[190:193], v[46:49]
	v_mfma_i32_16x16x64_i8 v[42:45], v[158:161], v[190:193], v[42:45]
	v_mfma_i32_16x16x64_i8 v[30:33], v[150:153], v[198:201], v[30:33]
	v_mfma_i32_16x16x64_i8 v[26:29], v[158:161], v[198:201], v[26:29]
	v_mfma_i32_16x16x64_i8 v[14:17], v[150:153], v[206:209], v[14:17]
	v_mfma_i32_16x16x64_i8 v[10:13], v[158:161], v[206:209], v[10:13]
	v_mfma_i32_16x16x64_i8 v[62:65], v[154:157], v[186:189], v[62:65]
	v_mfma_i32_16x16x64_i8 v[58:61], v[162:165], v[186:189], v[58:61]
	v_mfma_i32_16x16x64_i8 v[46:49], v[154:157], v[194:197], v[46:49]
	v_mfma_i32_16x16x64_i8 v[42:45], v[162:165], v[194:197], v[42:45]
	v_mfma_i32_16x16x64_i8 v[30:33], v[154:157], v[202:205], v[30:33]
	v_mfma_i32_16x16x64_i8 v[26:29], v[162:165], v[202:205], v[26:29]
	v_mfma_i32_16x16x64_i8 v[14:17], v[154:157], v[210:213], v[14:17]
	v_mfma_i32_16x16x64_i8 v[10:13], v[162:165], v[210:213], v[10:13]
	s_setprio 0
	s_setprio 1
	v_mfma_i32_16x16x64_i8 v[54:57], v[166:169], v[182:185], v[54:57]
	v_mfma_i32_16x16x64_i8 v[50:53], v[174:177], v[182:185], v[50:53]
	v_mfma_i32_16x16x64_i8 v[38:41], v[166:169], v[190:193], v[38:41]
	v_mfma_i32_16x16x64_i8 v[34:37], v[174:177], v[190:193], v[34:37]
	v_mfma_i32_16x16x64_i8 v[22:25], v[166:169], v[198:201], v[22:25]
	v_mfma_i32_16x16x64_i8 v[18:21], v[174:177], v[198:201], v[18:21]
	v_mfma_i32_16x16x64_i8 v[6:9], v[166:169], v[206:209], v[6:9]
	v_mfma_i32_16x16x64_i8 v[2:5], v[174:177], v[206:209], v[2:5]
	v_mfma_i32_16x16x64_i8 v[54:57], v[170:173], v[186:189], v[54:57]
	v_mfma_i32_16x16x64_i8 v[50:53], v[178:181], v[186:189], v[50:53]
	v_mfma_i32_16x16x64_i8 v[38:41], v[170:173], v[194:197], v[38:41]
	v_mfma_i32_16x16x64_i8 v[34:37], v[178:181], v[194:197], v[34:37]
	v_mfma_i32_16x16x64_i8 v[22:25], v[170:173], v[202:205], v[22:25]
	v_mfma_i32_16x16x64_i8 v[18:21], v[178:181], v[202:205], v[18:21]
	v_mfma_i32_16x16x64_i8 v[6:9], v[170:173], v[210:213], v[6:9]
	v_mfma_i32_16x16x64_i8 v[2:5], v[178:181], v[210:213], v[2:5]
	s_setprio 0
	s_barrier
	s_add_i32 s65, s65, 2
	s_add_u32 s48, s48, 0x100
	s_addc_u32 s49, s49, 0
	s_add_u32 s25, s25, 0x100
	s_addc_u32 s64, s64, 0
	s_cmp_gt_u32 s65, 5
	s_cbranch_scc0 .LBB0_445
	s_branch .Lpeel_exit_445
	.p2align	6

.LBB0_1316:
	v_add_u32_e32 v0, s16, v240
	ds_read_b64_tr_b16 v[192:193], v0 offset:24576
	ds_read_b64_tr_b16 v[194:195], v0 offset:25088
	v_add_f32_e32 v2, v80, v81
	v_add_f32_e32 v2, v82, v2
	v_add_f32_e32 v2, v83, v2
	v_add_f32_e32 v2, v84, v2
	v_add_f32_e32 v2, v85, v2
	v_cvt_pk_bf16_f32 v156, v80, v81
	v_cvt_pk_bf16_f32 v157, v82, v83
	s_waitcnt lgkmcnt(9)
	v_mfma_f32_32x32x16_bf16 v[96:111], v[188:191], v[140:143], v[48:63]
	ds_read_b64_tr_b16 v[188:189], v0 offset:28672
	ds_read_b64_tr_b16 v[190:191], v0 offset:29184
	v_add_f32_e32 v2, v86, v2
	v_add_f32_e32 v2, v87, v2
	v_add_f32_e32 v2, v88, v2
	v_add_f32_e32 v2, v89, v2
	v_cvt_pk_bf16_f32 v158, v84, v85
	v_cvt_pk_bf16_f32 v159, v86, v87
	s_waitcnt lgkmcnt(10)
	v_mfma_f32_32x32x16_bf16 v[112:127], v[184:187], v[140:143], v[48:63]
	ds_read_b64_tr_b16 v[10:11], v0 offset:25600
	ds_read_b64_tr_b16 v[12:13], v0 offset:26112
	v_add_f32_e32 v2, v90, v2
	v_add_f32_e32 v2, v91, v2
	v_add_f32_e32 v2, v92, v2
	v_add_f32_e32 v2, v93, v2
	v_cvt_pk_bf16_f32 v152, v88, v89
	v_cvt_pk_bf16_f32 v153, v90, v91
	s_waitcnt lgkmcnt(11)
	v_mfma_f32_32x32x16_bf16 v[96:111], v[180:183], v[136:139], v[96:111]
	ds_read_b64_tr_b16 v[180:181], v0 offset:29696
	ds_read_b64_tr_b16 v[182:183], v0 offset:30208
	v_add_f32_e32 v2, v94, v2
	v_add_f32_e32 v2, v95, v2
	v_add_f32_e32 v2, v64, v2
	v_add_f32_e32 v2, v65, v2
	v_cvt_pk_bf16_f32 v154, v92, v93
	v_cvt_pk_bf16_f32 v155, v94, v95
	s_waitcnt lgkmcnt(12)
	v_mfma_f32_32x32x16_bf16 v[112:127], v[176:179], v[136:139], v[112:127]
	ds_read_b64_tr_b16 v[176:177], v0 offset:26624
	ds_read_b64_tr_b16 v[178:179], v0 offset:27136
	v_add_f32_e32 v2, v66, v2
	v_add_f32_e32 v2, v67, v2
	v_add_f32_e32 v2, v68, v2
	v_add_f32_e32 v6, v69, v2
	v_cvt_pk_bf16_f32 v148, v64, v65
	v_cvt_pk_bf16_f32 v149, v66, v67
	ds_read_b128 v[64:67], v200
	s_waitcnt lgkmcnt(13)
	v_mfma_f32_32x32x16_bf16 v[96:111], v[172:175], v[132:135], v[96:111]
	ds_read_b64_tr_b16 v[2:3], v0 offset:30720
	ds_read_b64_tr_b16 v[4:5], v0 offset:31232
	v_add_f32_e32 v6, v70, v6
	v_add_f32_e32 v6, v71, v6
	v_add_f32_e32 v6, v72, v6
	v_add_f32_e32 v14, v73, v6
	v_cvt_pk_bf16_f32 v150, v68, v69
	v_cvt_pk_bf16_f32 v151, v70, v71
	ds_read_b128 v[68:71], v200 offset:32
	s_waitcnt lgkmcnt(14)
	v_mfma_f32_32x32x16_bf16 v[112:127], v[168:171], v[132:135], v[112:127]
	ds_read_b64_tr_b16 v[6:7], v0 offset:27648
	ds_read_b64_tr_b16 v[8:9], v0 offset:28160
	v_add_f32_e32 v14, v74, v14
	v_add_f32_e32 v14, v75, v14
	v_add_f32_e32 v14, v76, v14
	v_add_f32_e32 v14, v77, v14
	v_cvt_pk_bf16_f32 v144, v72, v73
	v_cvt_pk_bf16_f32 v145, v74, v75
	ds_read_b128 v[72:75], v200 offset:128
	s_waitcnt lgkmcnt(14)
	v_mfma_f32_32x32x16_bf16 v[96:111], v[164:167], v[128:131], v[96:111]
	ds_read_b64_tr_b16 v[164:165], v0 offset:31744
	ds_read_b64_tr_b16 v[166:167], v0 offset:32256
	v_add_f32_e32 v0, v78, v14
	v_add_f32_e32 v0, v79, v0
	v_add_f32_e32 v0, 0, v0
	v_cvt_pk_bf16_f32 v146, v76, v77
	v_cvt_pk_bf16_f32 v147, v78, v79
	v_mfma_f32_32x32x16_bf16 v[112:127], v[160:163], v[128:131], v[112:127]
	s_add_i32 s16, s46, -2
	s_lshr_b32 s16, s16, 2
	s_and_b32 s22, s47, 0x18000
	v_mad_u64_u32 v[14:15], s[16:17], s16, v239, v[212:213]
	s_lshl_b32 s26, s22, 1
	v_lshl_add_u64 v[14:15], v[14:15], 0, s[26:27]
	s_add_i32 s16, s50, s74
	s_mov_b32 s17, m0
	s_mov_b32 m0, s16
	s_nop 0
	global_load_lds_dwordx4 v[14:15], off
	s_mov_b32 m0, s17
	s_add_i32 s16, s46, -4
	s_add_i32 s17, s47, 0xffff0000
	s_lshr_b32 s16, s16, 2
	s_and_b32 s22, s17, 0x18000
	v_mad_u64_u32 v[14:15], s[16:17], s16, v239, v[214:215]
	s_lshl_b32 s26, s22, 1
	v_lshl_add_u64 v[14:15], v[14:15], 0, s[26:27]
	s_add_i32 s16, s25, s75
	s_mov_b32 s17, m0
	s_mov_b32 m0, s16
	s_nop 0
	global_load_lds_dwordx4 v[14:15], off
	s_mov_b32 m0, s17
	v_add_f32_e32 v0, v241, v0
	s_waitcnt lgkmcnt(2)
	v_add_f32_e32 v82, v98, v66
	v_add_f32_e32 v83, v99, v67
	s_waitcnt lgkmcnt(1)
	v_add_f32_e32 v84, v100, v68
	v_add_f32_e32 v85, v101, v69
	s_waitcnt lgkmcnt(0)
	v_add_f32_e32 v14, v112, v72
	v_add_f32_e32 v15, v113, v73
	v_add_f32_e32 v66, v114, v74
	v_add_f32_e32 v67, v115, v75
	ds_read_b128 v[72:75], v200 offset:160
	v_add_f32_e32 v86, v102, v70
	v_add_f32_e32 v87, v103, v71
	v_add_f32_e32 v64, v96, v64
	v_add_f32_e32 v65, v97, v65
	v_max3_f32 v81, v82, v83, v15
	v_max_f32_e32 v80, v64, v65
	s_waitcnt lgkmcnt(0)
	v_add_f32_e32 v68, v116, v72
	v_add_f32_e32 v69, v117, v73
	v_add_f32_e32 v70, v118, v74
	v_add_f32_e32 v71, v119, v75
	ds_read_b128 v[72:75], v200 offset:64
	ds_read_b128 v[76:79], v200 offset:192
	v_max3_f32 v80, v80, v14, v66
	v_max3_f32 v80, v80, v67, v84
	v_max3_f32 v81, v81, v86, v87
	s_waitcnt lgkmcnt(1)
	v_add_f32_e32 v88, v104, v72
	v_add_f32_e32 v89, v105, v73
	s_waitcnt lgkmcnt(0)
	v_add_f32_e32 v72, v120, v76
	v_add_f32_e32 v73, v121, v77
	v_add_f32_e32 v90, v106, v74
	v_add_f32_e32 v91, v107, v75
	v_add_f32_e32 v74, v122, v78
	v_add_f32_e32 v75, v123, v79
	ds_read_b128 v[76:79], v200 offset:96
	ds_read_b128 v[94:97], v200 offset:224
	v_max3_f32 v80, v80, v85, v68
	v_max3_f32 v81, v81, v70, v71
	v_max3_f32 v80, v80, v69, v88
	v_max3_f32 v81, v81, v90, v91
	s_waitcnt lgkmcnt(1)
	v_add_f32_e32 v92, v108, v76
	v_add_f32_e32 v93, v109, v77
	s_waitcnt lgkmcnt(0)
	v_add_f32_e32 v76, v124, v94
	v_add_f32_e32 v77, v125, v95
	v_add_f32_e32 v94, v110, v78
	v_add_f32_e32 v95, v111, v79
	v_max3_f32 v80, v80, v89, v72
	v_max3_f32 v81, v81, v74, v75
	v_add_f32_e32 v78, v126, v96
	v_add_f32_e32 v79, v127, v97
	v_max3_f32 v80, v80, v73, v92
	v_max3_f32 v81, v81, v94, v95
	v_max3_f32 v80, v80, v93, v76
	v_max3_f32 v81, v81, v78, v79
	v_max3_f32 v80, v80, v77, v81
	v_mov_b32_e32 v81, v80
	s_nop 1
	v_permlane32_swap_b32_e32 v80, v81
	v_max_f32_e32 v81, v81, v81
	v_max_f32_e32 v80, v80, v80
	v_max_f32_e32 v80, v80, v81
	v_cmp_lt_f32_e32 vcc, s36, v80
	s_cmp_lg_u64 vcc, 0
	s_cselect_b64 s[16:17], -1, 0
	s_cbranch_vccnz .LBB0_1324

.LBB0_1319:
	s_add_i32 s16, s25, 0x2000
	s_cmpk_lg_i32 s25, 0x4000
	s_cselect_b32 s78, s16, 0
	v_add_u32_e32 v14, s50, v240
	ds_read_b64_tr_b16 v[168:169], v14 offset:24576
	ds_read_b64_tr_b16 v[170:171], v14 offset:25088
	v_add_f32_e32 v2, v80, v81
	v_add_f32_e32 v2, v82, v2
	v_add_f32_e32 v2, v83, v2
	v_add_f32_e32 v2, v84, v2
	v_add_f32_e32 v2, v85, v2
	v_cvt_pk_bf16_f32 v156, v80, v81
	v_cvt_pk_bf16_f32 v157, v82, v83
	s_waitcnt lgkmcnt(9)
	v_mfma_f32_32x32x16_bf16 v[96:111], v[112:115], v[140:143], v[48:63]
	ds_read_b64_tr_b16 v[164:165], v14 offset:28672
	ds_read_b64_tr_b16 v[166:167], v14 offset:29184
	v_add_f32_e32 v2, v86, v2
	v_add_f32_e32 v2, v87, v2
	v_add_f32_e32 v2, v88, v2
	v_add_f32_e32 v2, v89, v2
	v_cvt_pk_bf16_f32 v158, v84, v85
	v_cvt_pk_bf16_f32 v159, v86, v87
	s_waitcnt lgkmcnt(10)
	v_mfma_f32_32x32x16_bf16 v[112:127], v[160:163], v[140:143], v[48:63]
	ds_read_b64_tr_b16 v[10:11], v14 offset:25600
	ds_read_b64_tr_b16 v[12:13], v14 offset:26112
	v_add_f32_e32 v2, v90, v2
	v_add_f32_e32 v2, v91, v2
	v_add_f32_e32 v2, v92, v2
	v_add_f32_e32 v2, v93, v2
	v_cvt_pk_bf16_f32 v152, v88, v89
	v_cvt_pk_bf16_f32 v153, v90, v91
	s_waitcnt lgkmcnt(11)
	v_mfma_f32_32x32x16_bf16 v[96:111], v[192:195], v[136:139], v[96:111]
	ds_read_b64_tr_b16 v[160:161], v14 offset:29696
	ds_read_b64_tr_b16 v[162:163], v14 offset:30208
	v_add_f32_e32 v2, v94, v2
	v_add_f32_e32 v2, v95, v2
	v_add_f32_e32 v2, v64, v2
	v_add_f32_e32 v2, v65, v2
	v_cvt_pk_bf16_f32 v154, v92, v93
	v_cvt_pk_bf16_f32 v155, v94, v95
	s_waitcnt lgkmcnt(12)
	v_mfma_f32_32x32x16_bf16 v[112:127], v[188:191], v[136:139], v[112:127]
	ds_read_b64_tr_b16 v[196:197], v14 offset:26624
	ds_read_b64_tr_b16 v[198:199], v14 offset:27136
	v_add_f32_e32 v2, v66, v2
	v_add_f32_e32 v2, v67, v2
	v_add_f32_e32 v2, v68, v2
	v_add_f32_e32 v6, v69, v2
	v_cvt_pk_bf16_f32 v148, v64, v65
	v_cvt_pk_bf16_f32 v149, v66, v67
	ds_read_b128 v[64:67], v200 offset:256
	s_waitcnt lgkmcnt(13)
	v_mfma_f32_32x32x16_bf16 v[96:111], v[184:187], v[132:135], v[96:111]
	ds_read_b64_tr_b16 v[2:3], v14 offset:30720
	ds_read_b64_tr_b16 v[4:5], v14 offset:31232
	v_add_f32_e32 v6, v70, v6
	v_add_f32_e32 v6, v71, v6
	v_add_f32_e32 v6, v72, v6
	v_add_f32_e32 v15, v73, v6
	v_cvt_pk_bf16_f32 v150, v68, v69
	v_cvt_pk_bf16_f32 v151, v70, v71
	ds_read_b128 v[68:71], v200 offset:288
	s_waitcnt lgkmcnt(14)
	v_mfma_f32_32x32x16_bf16 v[112:127], v[180:183], v[132:135], v[112:127]
	ds_read_b64_tr_b16 v[6:7], v14 offset:27648
	ds_read_b64_tr_b16 v[8:9], v14 offset:28160
	v_add_f32_e32 v15, v74, v15
	v_add_f32_e32 v15, v75, v15
	v_add_f32_e32 v15, v76, v15
	v_add_f32_e32 v15, v77, v15
	v_cvt_pk_bf16_f32 v144, v72, v73
	v_cvt_pk_bf16_f32 v145, v74, v75
	ds_read_b128 v[72:75], v200 offset:384
	s_waitcnt lgkmcnt(14)
	v_mfma_f32_32x32x16_bf16 v[96:111], v[176:179], v[128:131], v[96:111]
	ds_read_b64_tr_b16 v[192:193], v14 offset:31744
	ds_read_b64_tr_b16 v[194:195], v14 offset:32256
	v_add_f32_e32 v14, v78, v15
	v_add_f32_e32 v14, v79, v14
	v_add_f32_e32 v80, 0, v14
	v_cvt_pk_bf16_f32 v146, v76, v77
	v_cvt_pk_bf16_f32 v147, v78, v79
	v_mfma_f32_32x32x16_bf16 v[112:127], v[172:175], v[128:131], v[112:127]
	s_add_i32 s16, s46, -1
	s_add_i32 s17, s47, 0xfffe8000
	s_lshr_b32 s16, s16, 2
	s_and_b32 s22, s17, 0x18000
	v_mad_u64_u32 v[14:15], s[16:17], s16, v239, v[212:213]
	s_lshl_b32 s26, s22, 1
	v_lshl_add_u64 v[14:15], v[14:15], 0, s[26:27]
	s_add_i32 s16, s25, s74
	s_mov_b32 s17, m0
	s_mov_b32 m0, s16
	s_nop 0
	global_load_lds_dwordx4 v[14:15], off
	s_mov_b32 m0, s17
	s_add_i32 s50, s46, -3
	s_add_i32 s17, s47, 0xffff8000
	s_lshr_b32 s16, s50, 2
	s_and_b32 s22, s17, 0x18000
	v_mad_u64_u32 v[14:15], s[16:17], s16, v239, v[214:215]
	s_lshl_b32 s26, s22, 1
	v_lshl_add_u64 v[14:15], v[14:15], 0, s[26:27]
	s_add_i32 s16, s78, s75
	s_mov_b32 s17, m0
	s_mov_b32 m0, s16
	s_nop 0
	global_load_lds_dwordx4 v[14:15], off
	s_mov_b32 m0, s17
	v_add_f32_e32 v241, v0, v80
	s_waitcnt lgkmcnt(2)
	v_add_f32_e32 v82, v98, v66
	v_add_f32_e32 v83, v99, v67
	s_waitcnt lgkmcnt(1)
	v_add_f32_e32 v84, v100, v68
	v_add_f32_e32 v85, v101, v69
	s_waitcnt lgkmcnt(0)
	v_add_f32_e32 v14, v112, v72
	v_add_f32_e32 v15, v113, v73
	v_add_f32_e32 v66, v114, v74
	v_add_f32_e32 v67, v115, v75
	ds_read_b128 v[72:75], v200 offset:416
	v_add_f32_e32 v86, v102, v70
	v_add_f32_e32 v87, v103, v71
	v_add_f32_e32 v64, v96, v64
	v_add_f32_e32 v65, v97, v65
	s_waitcnt lgkmcnt(0)
	v_add_f32_e32 v68, v116, v72
	v_add_f32_e32 v69, v117, v73
	v_add_f32_e32 v70, v118, v74
	v_add_f32_e32 v71, v119, v75
	ds_read_b128 v[72:75], v200 offset:320
	ds_read_b128 v[76:79], v200 offset:448
	v_max_f32_e32 v81, v64, v65
	v_max3_f32 v81, v81, v14, v66
	v_max3_f32 v81, v81, v67, v84
	s_waitcnt lgkmcnt(1)
	v_add_f32_e32 v88, v104, v72
	v_add_f32_e32 v89, v105, v73
	s_waitcnt lgkmcnt(0)
	v_add_f32_e32 v72, v120, v76
	v_add_f32_e32 v73, v121, v77
	v_add_f32_e32 v90, v106, v74
	v_add_f32_e32 v91, v107, v75
	v_add_f32_e32 v74, v122, v78
	v_add_f32_e32 v75, v123, v79
	ds_read_b128 v[76:79], v200 offset:352
	ds_read_b128 v[94:97], v200 offset:480
	v_max3_f32 v81, v81, v85, v68
	v_max3_f32 v81, v81, v69, v88
	v_max3_f32 v81, v81, v89, v72
	s_waitcnt lgkmcnt(1)
	v_add_f32_e32 v92, v108, v76
	v_add_f32_e32 v93, v109, v77
	s_waitcnt lgkmcnt(0)
	v_add_f32_e32 v76, v124, v94
	v_add_f32_e32 v77, v125, v95
	v_add_f32_e32 v94, v110, v78
	v_add_f32_e32 v95, v111, v79
	v_add_f32_e32 v78, v126, v96
	v_add_f32_e32 v79, v127, v97
	v_max3_f32 v96, v82, v83, v15
	v_max3_f32 v96, v96, v86, v87
	v_max3_f32 v96, v96, v70, v71
	v_max3_f32 v96, v96, v90, v91
	v_max3_f32 v96, v96, v74, v75
	v_max3_f32 v81, v81, v73, v92
	v_max3_f32 v96, v96, v94, v95
	v_max3_f32 v81, v81, v93, v76
	v_max3_f32 v96, v96, v78, v79
	v_max3_f32 v0, v81, v77, v96
	v_mov_b32_e32 v80, v0
	s_nop 1
	v_permlane32_swap_b32_e32 v0, v80
	v_max_f32_e32 v80, v80, v80
	v_max_f32_e32 v0, v0, v0
	v_max_f32_e32 v0, v0, v80
	v_cmp_lt_f32_e32 vcc, s36, v0
	s_cmp_lg_u64 vcc, 0
	s_cselect_b64 s[16:17], -1, 0
	s_cbranch_vccnz .LBB0_1327
